# P1 f32 K/V/G output stores: permlane16/32 swaps so each store instruction writes 64 contiguous bytes per row (was 16B pieces at 32B stride); on top of v42
# baseline (speedup 1.0000x reference)
; __device__ __forceinline__ unsigned pk2(float lo, float hi) { f32x2 v = {lo, hi}; hbf2 r = __builtin_convertvector(v, hbf2); return __builtin_bit_cast(unsigned, r); }
;     __device__ __forceinline__ void operator()(const f32x4 (&acc)[2][2][4][2], const Unit& u, int wr, int wc, int fr, int fq) const {
;         const int sect = u.pn >> 1, cb = (u.pn & 1) * 256 + wc * 32 + 8 * fq, row0 = u.pm * 256 + wr * 64 + fr;
;         bf16* dst = act + (size_t)sect * ((size_t)M * HW);
;         const bool smp = row0 >= MP;
;         float* fo = nullptr;
;         if (sect == 1) fo = smp ? oks - (size_t)MP * HW : okp;
;         if (sect == 2) fo = smp ? ovs - (size_t)MP * HW : ovp;
;         if (sect == 4 && smp) fo = ogs - (size_t)MP * HW;
; #pragma unroll
;         for (int ai = 0; ai < 2; ++ai)
; #pragma unroll
;             for (int m = 0; m < 4; ++m) {
;                 const size_t off = (size_t)(row0 + ai * 128 + m * 16) * HW + cb;
; #pragma unroll
;                 for (int bj = 0; bj < 2; ++bj) {
;                     f32x4 v0 = acc[ai][bj][m][0], v1 = acc[ai][bj][m][1];
;                     if (sect == 0) { v0 = v0 * 0.125f; v1 = v1 * 0.125f; }
;                     if (sect >= 3) {
; #pragma unroll
;                         for (int e = 0; e < 4; ++e) { v0[e] = gelu_t(v0[e]); v1[e] = gelu_t(v1[e]); }
;                     }
;                     u32x4 w; w.x = pk2(v0[0], v0[1]); w.y = pk2(v0[2], v0[3]); w.z = pk2(v1[0], v1[1]); w.w = pk2(v1[2], v1[3]);
;                     *(u32x4*)(dst + off + bj * 128) = w;
;                     if (fo) { __builtin_nontemporal_store(v0, (f32x4*)(fo + off + bj * 128)); __builtin_nontemporal_store(v1, (f32x4*)(fo + off + bj * 128 + 4)); }
.LBB0_151:
	v_lshrrev_b32_e32 v200, 4, v160
	v_lshlrev_b32_e32 v200, 4, v200
	v_sub_u32_e32 v200, 0, v200
	v_ashrrev_i32_e32 v201, 31, v200
	s_ashr_i32 s11, s8, 1
	s_cmp_lt_u32 s8, 2
	v_pk_mul_f32 v[146:147], v[124:125], s[18:19] op_sel_hi:[1,0]
	s_cselect_b64 s[6:7], -1, 0
	s_cmp_gt_i32 s11, 2
	v_pk_mul_f32 v[148:149], v[126:127], s[18:19] op_sel_hi:[1,0]
	v_pk_mul_f32 v[150:151], v[122:123], s[18:19] op_sel_hi:[1,0]
	v_pk_mul_f32 v[154:155], v[120:121], s[18:19] op_sel_hi:[1,0]
	s_cselect_b64 s[40:41], -1, 0
	s_cmp_lt_i32 s11, 3
	v_cndmask_b32_e64 v125, v125, v147, s[6:7]
	v_cndmask_b32_e64 v124, v124, v146, s[6:7]
	v_cndmask_b32_e64 v127, v127, v149, s[6:7]
	v_cndmask_b32_e64 v126, v126, v148, s[6:7]
	v_cndmask_b32_e64 v121, v121, v155, s[6:7]
	v_cndmask_b32_e64 v120, v120, v154, s[6:7]
	v_cndmask_b32_e64 v123, v123, v151, s[6:7]
	v_cndmask_b32_e64 v122, v122, v150, s[6:7]
	s_cbranch_scc1 .LBB0_153
	v_mul_f32_e32 v146, 0x3d922279, v120
	v_fmaak_f32 v146, v120, v146, 0x3fcc422a
	v_mul_f32_e32 v136, 0x3d922279, v124
	v_mul_f32_e64 v146, v120, -v146
	v_fmaak_f32 v136, v124, v136, 0x3fcc422a
	v_mul_f32_e32 v146, 0x3fb8aa3b, v146
	v_mul_f32_e64 v136, v124, -v136
	v_exp_f32_e32 v147, v146
	v_mul_f32_e32 v146, 0x3d922279, v125
	v_mul_f32_e32 v136, 0x3fb8aa3b, v136
	v_fmaak_f32 v146, v125, v146, 0x3fcc422a
	v_exp_f32_e32 v136, v136
	v_mul_f32_e64 v146, v125, -v146
	v_mul_f32_e32 v146, 0x3fb8aa3b, v146
	v_exp_f32_e32 v149, v146
	v_add_f32_e32 v136, 1.0, v136
	v_rcp_f32_e32 v146, v136
	v_add_f32_e32 v136, 1.0, v147
	v_rcp_f32_e32 v148, v136
	v_add_f32_e32 v136, 1.0, v149
	v_mul_f32_e32 v149, 0x3d922279, v126
	v_fmaak_f32 v149, v126, v149, 0x3fcc422a
	v_mul_f32_e32 v150, 0x3d922279, v122
	v_mul_f32_e64 v149, v126, -v149
	v_fmaak_f32 v150, v122, v150, 0x3fcc422a
	v_mul_f32_e32 v149, 0x3fb8aa3b, v149
	v_mul_f32_e64 v150, v122, -v150
	v_exp_f32_e32 v149, v149
	v_mul_f32_e32 v150, 0x3fb8aa3b, v150
	v_exp_f32_e32 v151, v150
	v_rcp_f32_e32 v147, v136
	v_add_f32_e32 v149, 1.0, v149
	v_rcp_f32_e32 v150, v149
	v_add_f32_e32 v149, 1.0, v151
	v_mul_f32_e32 v151, 0x3d922279, v127
	v_mul_f32_e32 v136, 0x3d922279, v121
	v_fmaak_f32 v151, v127, v151, 0x3fcc422a
	v_mul_f32_e32 v154, 0x3d922279, v123
	v_fmaak_f32 v136, v121, v136, 0x3fcc422a
	v_mul_f32_e64 v151, v127, -v151
	v_fmaak_f32 v154, v123, v154, 0x3fcc422a
	v_mul_f32_e64 v136, v121, -v136
	v_mul_f32_e32 v151, 0x3fb8aa3b, v151
	v_mul_f32_e64 v154, v123, -v154
	v_mul_f32_e32 v136, 0x3fb8aa3b, v136
	v_exp_f32_e32 v151, v151
	v_mul_f32_e32 v154, 0x3fb8aa3b, v154
	v_exp_f32_e32 v136, v136
	v_exp_f32_e32 v155, v154
	v_rcp_f32_e32 v154, v149
	v_add_f32_e32 v149, 1.0, v151
	v_add_f32_e32 v136, 1.0, v136
	v_rcp_f32_e32 v151, v149
	v_add_f32_e32 v149, 1.0, v155
	v_rcp_f32_e32 v155, v149
	v_rcp_f32_e32 v149, v136
	v_pk_mul_f32 v[126:127], v[126:127], v[150:151]
	v_pk_mul_f32 v[124:125], v[124:125], v[146:147]
	v_pk_mul_f32 v[122:123], v[122:123], v[154:155]
	v_pk_mul_f32 v[120:121], v[120:121], v[148:149]
.LBB0_153:
	s_lshl_b32 s8, s8, 8
	s_and_b32 s8, s8, 0x100
	s_mul_i32 s9, s11, 0x1100000
	v_or_b32_e32 v170, s8, v163
	v_lshl_add_u32 v146, s10, 8, v157
	s_mul_hi_i32 s8, s11, 0x1100000
	s_add_u32 s38, s62, s9
	s_addc_u32 s39, s63, s8
	v_cmp_lt_i32_e32 vcc, s81, v146
	s_cmp_eq_u32 s11, 1
	s_cselect_b64 s[8:9], -1, 0
	v_cndmask_b32_e32 v136, v167, v168, vcc
	v_lshl_add_u64 v[148:149], s[58:59], 0, v[136:137]
	s_cmp_eq_u32 s11, 2
	v_cndmask_b32_e32 v136, v168, v169, vcc
	v_cndmask_b32_e64 v147, 0, v149, s[8:9]
	v_cndmask_b32_e64 v150, 0, v148, s[8:9]
	v_lshl_add_u64 v[148:149], s[58:59], 0, v[136:137]
	s_cselect_b64 s[8:9], -1, 0
	s_cmp_eq_u32 s11, 4
	v_cndmask_b32_e64 v136, v150, v148, s[8:9]
	v_cndmask_b32_e64 v147, v147, v149, s[8:9]
	s_cselect_b64 s[8:9], -1, 0
	v_mov_b32_e32 v148, s77
	s_and_b64 vcc, s[8:9], vcc
	v_cndmask_b32_e32 v149, v147, v148, vcc
	v_mov_b32_e32 v147, s76
	v_cndmask_b32_e32 v148, v136, v147, vcc
	v_ashrrev_i32_e32 v147, 31, v146
	v_lshlrev_b64 v[150:151], 9, v[146:147]
	v_or_b32_e32 v150, v150, v170
	v_cmp_ne_u64_e64 s[8:9], 0, v[148:149]
	v_lshl_add_u64 v[154:155], v[150:151], 1, s[38:39]
	v_lshl_add_u64 v[150:151], v[150:151], 2, v[148:149]
	v_cvt_pk_bf16_f32 v172, v124, v125
	v_cvt_pk_bf16_f32 v173, v126, v127
	v_cvt_pk_bf16_f32 v174, v120, v121
	v_cvt_pk_bf16_f32 v175, v122, v123
	global_store_dwordx4 v[154:155], v[172:175], off
	s_and_saveexec_b64 s[10:11], s[8:9]
	s_cbranch_execz .LBB0_155
	s_nop 1
	v_permlane16_swap_b32_e32 v124, v120
	v_permlane16_swap_b32_e32 v125, v121
	v_permlane16_swap_b32_e32 v126, v122
	v_permlane16_swap_b32_e32 v127, v123
	v_permlane32_swap_b32_e32 v124, v120
	v_permlane32_swap_b32_e32 v125, v121
	v_permlane32_swap_b32_e32 v126, v122
	v_permlane32_swap_b32_e32 v127, v123
	v_lshl_add_u64 v[202:203], v[150:151], 0, v[200:201]
	global_store_dwordx4 v[202:203], v[124:127], off
	global_store_dwordx4 v[202:203], v[120:123], off offset:64

; __device__ __forceinline__ unsigned pk2(float lo, float hi) { f32x2 v = {lo, hi}; hbf2 r = __builtin_convertvector(v, hbf2); return __builtin_bit_cast(unsigned, r); }
;     __device__ __forceinline__ void operator()(const f32x4 (&acc)[2][2][4][2], const Unit& u, int wr, int wc, int fr, int fq) const {
;     ...
;                     u32x4 w; w.x = pk2(v0[0], v0[1]); w.y = pk2(v0[2], v0[3]); w.z = pk2(v1[0], v1[1]); w.w = pk2(v1[2], v1[3]);
;                     *(u32x4*)(dst + off + bj * 128) = w;
;                     if (fo) { __builtin_nontemporal_store(v0, (f32x4*)(fo + off + bj * 128)); __builtin_nontemporal_store(v1, (f32x4*)(fo + off + bj * 128 + 4)); }
.LBB0_157:
	v_cvt_pk_bf16_f32 v120, v116, v117
	v_cvt_pk_bf16_f32 v121, v118, v119
	v_cvt_pk_bf16_f32 v122, v112, v113
	v_cvt_pk_bf16_f32 v123, v114, v115
	global_store_dwordx4 v[154:155], v[120:123], off offset:256
	s_and_saveexec_b64 s[40:41], s[8:9]
	s_cbranch_execz .LBB0_159
	s_nop 1
	v_permlane16_swap_b32_e32 v116, v112
	v_permlane16_swap_b32_e32 v117, v113
	v_permlane16_swap_b32_e32 v118, v114
	v_permlane16_swap_b32_e32 v119, v115
	v_permlane32_swap_b32_e32 v116, v112
	v_permlane32_swap_b32_e32 v117, v113
	v_permlane32_swap_b32_e32 v118, v114
	v_permlane32_swap_b32_e32 v119, v115
	v_lshl_add_u64 v[202:203], v[150:151], 0, v[200:201]
	global_store_dwordx4 v[202:203], v[116:119], off offset:512
	global_store_dwordx4 v[202:203], v[112:115], off offset:576

; __device__ __forceinline__ unsigned pk2(float lo, float hi) { f32x2 v = {lo, hi}; hbf2 r = __builtin_convertvector(v, hbf2); return __builtin_bit_cast(unsigned, r); }
;     __device__ __forceinline__ void operator()(const f32x4 (&acc)[2][2][4][2], const Unit& u, int wr, int wc, int fr, int fq) const {
;     ...
;                 const size_t off = (size_t)(row0 + ai * 128 + m * 16) * HW + cb;
; #pragma unroll
;                 for (int bj = 0; bj < 2; ++bj) {
;                     f32x4 v0 = acc[ai][bj][m][0], v1 = acc[ai][bj][m][1];
;                     if (sect == 0) { v0 = v0 * 0.125f; v1 = v1 * 0.125f; }
;                     if (sect >= 3) {
; #pragma unroll
;                         for (int e = 0; e < 4; ++e) { v0[e] = gelu_t(v0[e]); v1[e] = gelu_t(v1[e]); }
;                     }
;                     u32x4 w; w.x = pk2(v0[0], v0[1]); w.y = pk2(v0[2], v0[3]); w.z = pk2(v1[0], v1[1]); w.w = pk2(v1[2], v1[3]);
;                     *(u32x4*)(dst + off + bj * 128) = w;
;                     if (fo) { __builtin_nontemporal_store(v0, (f32x4*)(fo + off + bj * 128)); __builtin_nontemporal_store(v1, (f32x4*)(fo + off + bj * 128 + 4)); }
.LBB0_161:
	v_or_b32_e32 v112, 16, v146
	v_ashrrev_i32_e32 v113, 31, v112
	v_lshlrev_b64 v[112:113], 9, v[112:113]
	v_or_b32_e32 v112, v112, v170
	v_lshl_add_u64 v[114:115], v[112:113], 1, s[38:39]
	v_lshl_add_u64 v[112:113], v[112:113], 2, v[148:149]
	v_cvt_pk_bf16_f32 v116, v108, v109
	v_cvt_pk_bf16_f32 v117, v110, v111
	v_cvt_pk_bf16_f32 v118, v104, v105
	v_cvt_pk_bf16_f32 v119, v106, v107
	global_store_dwordx4 v[114:115], v[116:119], off
	s_and_saveexec_b64 s[40:41], s[8:9]
	s_cbranch_execz .LBB0_163
	s_nop 1
	v_permlane16_swap_b32_e32 v108, v104
	v_permlane16_swap_b32_e32 v109, v105
	v_permlane16_swap_b32_e32 v110, v106
	v_permlane16_swap_b32_e32 v111, v107
	v_permlane32_swap_b32_e32 v108, v104
	v_permlane32_swap_b32_e32 v109, v105
	v_permlane32_swap_b32_e32 v110, v106
	v_permlane32_swap_b32_e32 v111, v107
	v_lshl_add_u64 v[202:203], v[112:113], 0, v[200:201]
	global_store_dwordx4 v[202:203], v[108:111], off
	global_store_dwordx4 v[202:203], v[104:107], off offset:64

; __device__ __forceinline__ unsigned pk2(float lo, float hi) { f32x2 v = {lo, hi}; hbf2 r = __builtin_convertvector(v, hbf2); return __builtin_bit_cast(unsigned, r); }
;     __device__ __forceinline__ void operator()(const f32x4 (&acc)[2][2][4][2], const Unit& u, int wr, int wc, int fr, int fq) const {
;     ...
;                     u32x4 w; w.x = pk2(v0[0], v0[1]); w.y = pk2(v0[2], v0[3]); w.z = pk2(v1[0], v1[1]); w.w = pk2(v1[2], v1[3]);
;                     *(u32x4*)(dst + off + bj * 128) = w;
;                     if (fo) { __builtin_nontemporal_store(v0, (f32x4*)(fo + off + bj * 128)); __builtin_nontemporal_store(v1, (f32x4*)(fo + off + bj * 128 + 4)); }
.LBB0_165:
	v_cvt_pk_bf16_f32 v104, v100, v101
	v_cvt_pk_bf16_f32 v105, v102, v103
	v_cvt_pk_bf16_f32 v106, v96, v97
	v_cvt_pk_bf16_f32 v107, v98, v99
	global_store_dwordx4 v[114:115], v[104:107], off offset:256
	s_and_saveexec_b64 s[40:41], s[8:9]
	s_cbranch_execz .LBB0_167
	s_nop 1
	v_permlane16_swap_b32_e32 v100, v96
	v_permlane16_swap_b32_e32 v101, v97
	v_permlane16_swap_b32_e32 v102, v98
	v_permlane16_swap_b32_e32 v103, v99
	v_permlane32_swap_b32_e32 v100, v96
	v_permlane32_swap_b32_e32 v101, v97
	v_permlane32_swap_b32_e32 v102, v98
	v_permlane32_swap_b32_e32 v103, v99
	v_lshl_add_u64 v[202:203], v[112:113], 0, v[200:201]
	global_store_dwordx4 v[202:203], v[100:103], off offset:512
	global_store_dwordx4 v[202:203], v[96:99], off offset:576

; __device__ __forceinline__ unsigned pk2(float lo, float hi) { f32x2 v = {lo, hi}; hbf2 r = __builtin_convertvector(v, hbf2); return __builtin_bit_cast(unsigned, r); }
;     __device__ __forceinline__ void operator()(const f32x4 (&acc)[2][2][4][2], const Unit& u, int wr, int wc, int fr, int fq) const {
;     ...
;                 const size_t off = (size_t)(row0 + ai * 128 + m * 16) * HW + cb;
; #pragma unroll
;                 for (int bj = 0; bj < 2; ++bj) {
;                     f32x4 v0 = acc[ai][bj][m][0], v1 = acc[ai][bj][m][1];
;                     if (sect == 0) { v0 = v0 * 0.125f; v1 = v1 * 0.125f; }
;                     if (sect >= 3) {
; #pragma unroll
;                         for (int e = 0; e < 4; ++e) { v0[e] = gelu_t(v0[e]); v1[e] = gelu_t(v1[e]); }
;                     }
;                     u32x4 w; w.x = pk2(v0[0], v0[1]); w.y = pk2(v0[2], v0[3]); w.z = pk2(v1[0], v1[1]); w.w = pk2(v1[2], v1[3]);
;                     *(u32x4*)(dst + off + bj * 128) = w;
;                     if (fo) { __builtin_nontemporal_store(v0, (f32x4*)(fo + off + bj * 128)); __builtin_nontemporal_store(v1, (f32x4*)(fo + off + bj * 128 + 4)); }
.LBB0_169:
	v_or_b32_e32 v96, 32, v146
	v_ashrrev_i32_e32 v97, 31, v96
	v_lshlrev_b64 v[96:97], 9, v[96:97]
	v_or_b32_e32 v96, v96, v170
	v_lshl_add_u64 v[98:99], v[96:97], 1, s[38:39]
	v_lshl_add_u64 v[96:97], v[96:97], 2, v[148:149]
	v_cvt_pk_bf16_f32 v100, v92, v93
	v_cvt_pk_bf16_f32 v101, v94, v95
	v_cvt_pk_bf16_f32 v102, v88, v89
	v_cvt_pk_bf16_f32 v103, v90, v91
	global_store_dwordx4 v[98:99], v[100:103], off
	s_and_saveexec_b64 s[40:41], s[8:9]
	s_cbranch_execz .LBB0_171
	s_nop 1
	v_permlane16_swap_b32_e32 v92, v88
	v_permlane16_swap_b32_e32 v93, v89
	v_permlane16_swap_b32_e32 v94, v90
	v_permlane16_swap_b32_e32 v95, v91
	v_permlane32_swap_b32_e32 v92, v88
	v_permlane32_swap_b32_e32 v93, v89
	v_permlane32_swap_b32_e32 v94, v90
	v_permlane32_swap_b32_e32 v95, v91
	v_lshl_add_u64 v[202:203], v[96:97], 0, v[200:201]
	global_store_dwordx4 v[202:203], v[92:95], off
	global_store_dwordx4 v[202:203], v[88:91], off offset:64

; __device__ __forceinline__ unsigned pk2(float lo, float hi) { f32x2 v = {lo, hi}; hbf2 r = __builtin_convertvector(v, hbf2); return __builtin_bit_cast(unsigned, r); }
;     __device__ __forceinline__ void operator()(const f32x4 (&acc)[2][2][4][2], const Unit& u, int wr, int wc, int fr, int fq) const {
;     ...
;                     u32x4 w; w.x = pk2(v0[0], v0[1]); w.y = pk2(v0[2], v0[3]); w.z = pk2(v1[0], v1[1]); w.w = pk2(v1[2], v1[3]);
;                     *(u32x4*)(dst + off + bj * 128) = w;
;                     if (fo) { __builtin_nontemporal_store(v0, (f32x4*)(fo + off + bj * 128)); __builtin_nontemporal_store(v1, (f32x4*)(fo + off + bj * 128 + 4)); }
.LBB0_173:
	v_cvt_pk_bf16_f32 v88, v84, v85
	v_cvt_pk_bf16_f32 v89, v86, v87
	v_cvt_pk_bf16_f32 v90, v80, v81
	v_cvt_pk_bf16_f32 v91, v82, v83
	global_store_dwordx4 v[98:99], v[88:91], off offset:256
	s_and_saveexec_b64 s[40:41], s[8:9]
	s_cbranch_execz .LBB0_175
	s_nop 1
	v_permlane16_swap_b32_e32 v84, v80
	v_permlane16_swap_b32_e32 v85, v81
	v_permlane16_swap_b32_e32 v86, v82
	v_permlane16_swap_b32_e32 v87, v83
	v_permlane32_swap_b32_e32 v84, v80
	v_permlane32_swap_b32_e32 v85, v81
	v_permlane32_swap_b32_e32 v86, v82
	v_permlane32_swap_b32_e32 v87, v83
	v_lshl_add_u64 v[202:203], v[96:97], 0, v[200:201]
	global_store_dwordx4 v[202:203], v[84:87], off offset:512
	global_store_dwordx4 v[202:203], v[80:83], off offset:576

; __device__ __forceinline__ unsigned pk2(float lo, float hi) { f32x2 v = {lo, hi}; hbf2 r = __builtin_convertvector(v, hbf2); return __builtin_bit_cast(unsigned, r); }
;     __device__ __forceinline__ void operator()(const f32x4 (&acc)[2][2][4][2], const Unit& u, int wr, int wc, int fr, int fq) const {
;     ...
;                 const size_t off = (size_t)(row0 + ai * 128 + m * 16) * HW + cb;
; #pragma unroll
;                 for (int bj = 0; bj < 2; ++bj) {
;                     f32x4 v0 = acc[ai][bj][m][0], v1 = acc[ai][bj][m][1];
;                     if (sect == 0) { v0 = v0 * 0.125f; v1 = v1 * 0.125f; }
;                     if (sect >= 3) {
; #pragma unroll
;                         for (int e = 0; e < 4; ++e) { v0[e] = gelu_t(v0[e]); v1[e] = gelu_t(v1[e]); }
;                     }
;                     u32x4 w; w.x = pk2(v0[0], v0[1]); w.y = pk2(v0[2], v0[3]); w.z = pk2(v1[0], v1[1]); w.w = pk2(v1[2], v1[3]);
;                     *(u32x4*)(dst + off + bj * 128) = w;
;                     if (fo) { __builtin_nontemporal_store(v0, (f32x4*)(fo + off + bj * 128)); __builtin_nontemporal_store(v1, (f32x4*)(fo + off + bj * 128 + 4)); }
.LBB0_177:
	v_or_b32_e32 v80, 48, v146
	v_ashrrev_i32_e32 v81, 31, v80
	v_lshlrev_b64 v[80:81], 9, v[80:81]
	v_or_b32_e32 v80, v80, v170
	v_lshl_add_u64 v[82:83], v[80:81], 1, s[38:39]
	v_lshl_add_u64 v[80:81], v[80:81], 2, v[148:149]
	v_cvt_pk_bf16_f32 v84, v76, v77
	v_cvt_pk_bf16_f32 v85, v78, v79
	v_cvt_pk_bf16_f32 v86, v72, v73
	v_cvt_pk_bf16_f32 v87, v74, v75
	global_store_dwordx4 v[82:83], v[84:87], off
	s_and_saveexec_b64 s[40:41], s[8:9]
	s_cbranch_execz .LBB0_179
	s_nop 1
	v_permlane16_swap_b32_e32 v76, v72
	v_permlane16_swap_b32_e32 v77, v73
	v_permlane16_swap_b32_e32 v78, v74
	v_permlane16_swap_b32_e32 v79, v75
	v_permlane32_swap_b32_e32 v76, v72
	v_permlane32_swap_b32_e32 v77, v73
	v_permlane32_swap_b32_e32 v78, v74
	v_permlane32_swap_b32_e32 v79, v75
	v_lshl_add_u64 v[202:203], v[80:81], 0, v[200:201]
	global_store_dwordx4 v[202:203], v[76:79], off
	global_store_dwordx4 v[202:203], v[72:75], off offset:64

; __device__ __forceinline__ unsigned pk2(float lo, float hi) { f32x2 v = {lo, hi}; hbf2 r = __builtin_convertvector(v, hbf2); return __builtin_bit_cast(unsigned, r); }
;     __device__ __forceinline__ void operator()(const f32x4 (&acc)[2][2][4][2], const Unit& u, int wr, int wc, int fr, int fq) const {
;     ...
;                     u32x4 w; w.x = pk2(v0[0], v0[1]); w.y = pk2(v0[2], v0[3]); w.z = pk2(v1[0], v1[1]); w.w = pk2(v1[2], v1[3]);
;                     *(u32x4*)(dst + off + bj * 128) = w;
;                     if (fo) { __builtin_nontemporal_store(v0, (f32x4*)(fo + off + bj * 128)); __builtin_nontemporal_store(v1, (f32x4*)(fo + off + bj * 128 + 4)); }
.LBB0_181:
	v_cvt_pk_bf16_f32 v72, v68, v69
	v_cvt_pk_bf16_f32 v73, v70, v71
	v_cvt_pk_bf16_f32 v74, v64, v65
	v_cvt_pk_bf16_f32 v75, v66, v67
	global_store_dwordx4 v[82:83], v[72:75], off offset:256
	s_and_saveexec_b64 s[40:41], s[8:9]
	s_cbranch_execz .LBB0_183
	s_nop 1
	v_permlane16_swap_b32_e32 v68, v64
	v_permlane16_swap_b32_e32 v69, v65
	v_permlane16_swap_b32_e32 v70, v66
	v_permlane16_swap_b32_e32 v71, v67
	v_permlane32_swap_b32_e32 v68, v64
	v_permlane32_swap_b32_e32 v69, v65
	v_permlane32_swap_b32_e32 v70, v66
	v_permlane32_swap_b32_e32 v71, v67
	v_lshl_add_u64 v[202:203], v[80:81], 0, v[200:201]
	global_store_dwordx4 v[202:203], v[68:71], off offset:512
	global_store_dwordx4 v[202:203], v[64:67], off offset:576

; __device__ __forceinline__ unsigned pk2(float lo, float hi) { f32x2 v = {lo, hi}; hbf2 r = __builtin_convertvector(v, hbf2); return __builtin_bit_cast(unsigned, r); }
;     __device__ __forceinline__ void operator()(const f32x4 (&acc)[2][2][4][2], const Unit& u, int wr, int wc, int fr, int fq) const {
;     ...
;                 const size_t off = (size_t)(row0 + ai * 128 + m * 16) * HW + cb;
; #pragma unroll
;                 for (int bj = 0; bj < 2; ++bj) {
;                     f32x4 v0 = acc[ai][bj][m][0], v1 = acc[ai][bj][m][1];
;                     if (sect == 0) { v0 = v0 * 0.125f; v1 = v1 * 0.125f; }
;                     if (sect >= 3) {
; #pragma unroll
;                         for (int e = 0; e < 4; ++e) { v0[e] = gelu_t(v0[e]); v1[e] = gelu_t(v1[e]); }
;                     }
;                     u32x4 w; w.x = pk2(v0[0], v0[1]); w.y = pk2(v0[2], v0[3]); w.z = pk2(v1[0], v1[1]); w.w = pk2(v1[2], v1[3]);
;                     *(u32x4*)(dst + off + bj * 128) = w;
;                     if (fo) { __builtin_nontemporal_store(v0, (f32x4*)(fo + off + bj * 128)); __builtin_nontemporal_store(v1, (f32x4*)(fo + off + bj * 128 + 4)); }
.LBB0_185:
	v_lshlrev_b64 v[64:65], 9, v[146:147]
	v_or_b32_e32 v64, v64, v170
	v_lshl_add_u64 v[64:65], v[64:65], 0, s[20:21]
	v_lshl_add_u64 v[66:67], v[64:65], 1, s[38:39]
	v_lshl_add_u64 v[64:65], v[64:65], 2, v[148:149]
	v_cvt_pk_bf16_f32 v68, v60, v61
	v_cvt_pk_bf16_f32 v69, v62, v63
	v_cvt_pk_bf16_f32 v70, v56, v57
	v_cvt_pk_bf16_f32 v71, v58, v59
	global_store_dwordx4 v[66:67], v[68:71], off
	s_and_saveexec_b64 s[40:41], s[8:9]
	s_cbranch_execz .LBB0_187
	s_nop 1
	v_permlane16_swap_b32_e32 v60, v56
	v_permlane16_swap_b32_e32 v61, v57
	v_permlane16_swap_b32_e32 v62, v58
	v_permlane16_swap_b32_e32 v63, v59
	v_permlane32_swap_b32_e32 v60, v56
	v_permlane32_swap_b32_e32 v61, v57
	v_permlane32_swap_b32_e32 v62, v58
	v_permlane32_swap_b32_e32 v63, v59
	v_lshl_add_u64 v[202:203], v[64:65], 0, v[200:201]
	global_store_dwordx4 v[202:203], v[60:63], off
	global_store_dwordx4 v[202:203], v[56:59], off offset:64

; __device__ __forceinline__ unsigned pk2(float lo, float hi) { f32x2 v = {lo, hi}; hbf2 r = __builtin_convertvector(v, hbf2); return __builtin_bit_cast(unsigned, r); }
;     __device__ __forceinline__ void operator()(const f32x4 (&acc)[2][2][4][2], const Unit& u, int wr, int wc, int fr, int fq) const {
;     ...
;                     u32x4 w; w.x = pk2(v0[0], v0[1]); w.y = pk2(v0[2], v0[3]); w.z = pk2(v1[0], v1[1]); w.w = pk2(v1[2], v1[3]);
;                     *(u32x4*)(dst + off + bj * 128) = w;
;                     if (fo) { __builtin_nontemporal_store(v0, (f32x4*)(fo + off + bj * 128)); __builtin_nontemporal_store(v1, (f32x4*)(fo + off + bj * 128 + 4)); }
.LBB0_189:
	v_cvt_pk_bf16_f32 v56, v52, v53
	v_cvt_pk_bf16_f32 v57, v54, v55
	v_cvt_pk_bf16_f32 v58, v48, v49
	v_cvt_pk_bf16_f32 v59, v50, v51
	global_store_dwordx4 v[66:67], v[56:59], off offset:256
	s_and_saveexec_b64 s[40:41], s[8:9]
	s_cbranch_execz .LBB0_191
	s_nop 1
	v_permlane16_swap_b32_e32 v52, v48
	v_permlane16_swap_b32_e32 v53, v49
	v_permlane16_swap_b32_e32 v54, v50
	v_permlane16_swap_b32_e32 v55, v51
	v_permlane32_swap_b32_e32 v52, v48
	v_permlane32_swap_b32_e32 v53, v49
	v_permlane32_swap_b32_e32 v54, v50
	v_permlane32_swap_b32_e32 v55, v51
	v_lshl_add_u64 v[202:203], v[64:65], 0, v[200:201]
	global_store_dwordx4 v[202:203], v[52:55], off offset:512
	global_store_dwordx4 v[202:203], v[48:51], off offset:576

; __device__ __forceinline__ unsigned pk2(float lo, float hi) { f32x2 v = {lo, hi}; hbf2 r = __builtin_convertvector(v, hbf2); return __builtin_bit_cast(unsigned, r); }
;     __device__ __forceinline__ void operator()(const f32x4 (&acc)[2][2][4][2], const Unit& u, int wr, int wc, int fr, int fq) const {
;     ...
;                 const size_t off = (size_t)(row0 + ai * 128 + m * 16) * HW + cb;
; #pragma unroll
;                 for (int bj = 0; bj < 2; ++bj) {
;                     f32x4 v0 = acc[ai][bj][m][0], v1 = acc[ai][bj][m][1];
;                     if (sect == 0) { v0 = v0 * 0.125f; v1 = v1 * 0.125f; }
;                     if (sect >= 3) {
; #pragma unroll
;                         for (int e = 0; e < 4; ++e) { v0[e] = gelu_t(v0[e]); v1[e] = gelu_t(v1[e]); }
;                     }
;                     u32x4 w; w.x = pk2(v0[0], v0[1]); w.y = pk2(v0[2], v0[3]); w.z = pk2(v1[0], v1[1]); w.w = pk2(v1[2], v1[3]);
;                     *(u32x4*)(dst + off + bj * 128) = w;
;                     if (fo) { __builtin_nontemporal_store(v0, (f32x4*)(fo + off + bj * 128)); __builtin_nontemporal_store(v1, (f32x4*)(fo + off + bj * 128 + 4)); }
.LBB0_193:
	v_lshlrev_b64 v[48:49], 9, v[146:147]
	v_or_b32_e32 v48, v48, v170
	v_lshl_add_u64 v[48:49], v[48:49], 0, s[22:23]
	v_lshl_add_u64 v[50:51], v[48:49], 1, s[38:39]
	v_lshl_add_u64 v[48:49], v[48:49], 2, v[148:149]
	v_cvt_pk_bf16_f32 v52, v44, v45
	v_cvt_pk_bf16_f32 v53, v46, v47
	v_cvt_pk_bf16_f32 v54, v40, v41
	v_cvt_pk_bf16_f32 v55, v42, v43
	global_store_dwordx4 v[50:51], v[52:55], off
	s_and_saveexec_b64 s[40:41], s[8:9]
	s_cbranch_execz .LBB0_195
	s_nop 1
	v_permlane16_swap_b32_e32 v44, v40
	v_permlane16_swap_b32_e32 v45, v41
	v_permlane16_swap_b32_e32 v46, v42
	v_permlane16_swap_b32_e32 v47, v43
	v_permlane32_swap_b32_e32 v44, v40
	v_permlane32_swap_b32_e32 v45, v41
	v_permlane32_swap_b32_e32 v46, v42
	v_permlane32_swap_b32_e32 v47, v43
	v_lshl_add_u64 v[202:203], v[48:49], 0, v[200:201]
	global_store_dwordx4 v[202:203], v[44:47], off
	global_store_dwordx4 v[202:203], v[40:43], off offset:64

; __device__ __forceinline__ unsigned pk2(float lo, float hi) { f32x2 v = {lo, hi}; hbf2 r = __builtin_convertvector(v, hbf2); return __builtin_bit_cast(unsigned, r); }
;     __device__ __forceinline__ void operator()(const f32x4 (&acc)[2][2][4][2], const Unit& u, int wr, int wc, int fr, int fq) const {
;     ...
;                     u32x4 w; w.x = pk2(v0[0], v0[1]); w.y = pk2(v0[2], v0[3]); w.z = pk2(v1[0], v1[1]); w.w = pk2(v1[2], v1[3]);
;                     *(u32x4*)(dst + off + bj * 128) = w;
;                     if (fo) { __builtin_nontemporal_store(v0, (f32x4*)(fo + off + bj * 128)); __builtin_nontemporal_store(v1, (f32x4*)(fo + off + bj * 128 + 4)); }
.LBB0_197:
	v_cvt_pk_bf16_f32 v40, v36, v37
	v_cvt_pk_bf16_f32 v41, v38, v39
	v_cvt_pk_bf16_f32 v42, v32, v33
	v_cvt_pk_bf16_f32 v43, v34, v35
	global_store_dwordx4 v[50:51], v[40:43], off offset:256
	s_and_saveexec_b64 s[40:41], s[8:9]
	s_cbranch_execz .LBB0_199
	s_nop 1
	v_permlane16_swap_b32_e32 v36, v32
	v_permlane16_swap_b32_e32 v37, v33
	v_permlane16_swap_b32_e32 v38, v34
	v_permlane16_swap_b32_e32 v39, v35
	v_permlane32_swap_b32_e32 v36, v32
	v_permlane32_swap_b32_e32 v37, v33
	v_permlane32_swap_b32_e32 v38, v34
	v_permlane32_swap_b32_e32 v39, v35
	v_lshl_add_u64 v[202:203], v[48:49], 0, v[200:201]
	global_store_dwordx4 v[202:203], v[36:39], off offset:512
	global_store_dwordx4 v[202:203], v[32:35], off offset:576

; __device__ __forceinline__ unsigned pk2(float lo, float hi) { f32x2 v = {lo, hi}; hbf2 r = __builtin_convertvector(v, hbf2); return __builtin_bit_cast(unsigned, r); }
;     __device__ __forceinline__ void operator()(const f32x4 (&acc)[2][2][4][2], const Unit& u, int wr, int wc, int fr, int fq) const {
;     ...
;                 const size_t off = (size_t)(row0 + ai * 128 + m * 16) * HW + cb;
; #pragma unroll
;                 for (int bj = 0; bj < 2; ++bj) {
;                     f32x4 v0 = acc[ai][bj][m][0], v1 = acc[ai][bj][m][1];
;                     if (sect == 0) { v0 = v0 * 0.125f; v1 = v1 * 0.125f; }
;                     if (sect >= 3) {
; #pragma unroll
;                         for (int e = 0; e < 4; ++e) { v0[e] = gelu_t(v0[e]); v1[e] = gelu_t(v1[e]); }
;                     }
;                     u32x4 w; w.x = pk2(v0[0], v0[1]); w.y = pk2(v0[2], v0[3]); w.z = pk2(v1[0], v1[1]); w.w = pk2(v1[2], v1[3]);
;                     *(u32x4*)(dst + off + bj * 128) = w;
;                     if (fo) { __builtin_nontemporal_store(v0, (f32x4*)(fo + off + bj * 128)); __builtin_nontemporal_store(v1, (f32x4*)(fo + off + bj * 128 + 4)); }
.LBB0_201:
	v_lshlrev_b64 v[32:33], 9, v[146:147]
	v_or_b32_e32 v32, v32, v170
	v_lshl_add_u64 v[32:33], v[32:33], 0, s[24:25]
	v_lshl_add_u64 v[34:35], v[32:33], 1, s[38:39]
	v_lshl_add_u64 v[32:33], v[32:33], 2, v[148:149]
	v_cvt_pk_bf16_f32 v36, v28, v29
	v_cvt_pk_bf16_f32 v37, v30, v31
	v_cvt_pk_bf16_f32 v38, v24, v25
	v_cvt_pk_bf16_f32 v39, v26, v27
	global_store_dwordx4 v[34:35], v[36:39], off
	s_and_saveexec_b64 s[40:41], s[8:9]
	s_cbranch_execz .LBB0_203
	s_nop 1
	v_permlane16_swap_b32_e32 v28, v24
	v_permlane16_swap_b32_e32 v29, v25
	v_permlane16_swap_b32_e32 v30, v26
	v_permlane16_swap_b32_e32 v31, v27
	v_permlane32_swap_b32_e32 v28, v24
	v_permlane32_swap_b32_e32 v29, v25
	v_permlane32_swap_b32_e32 v30, v26
	v_permlane32_swap_b32_e32 v31, v27
	v_lshl_add_u64 v[202:203], v[32:33], 0, v[200:201]
	global_store_dwordx4 v[202:203], v[28:31], off
	global_store_dwordx4 v[202:203], v[24:27], off offset:64

; __device__ __forceinline__ unsigned pk2(float lo, float hi) { f32x2 v = {lo, hi}; hbf2 r = __builtin_convertvector(v, hbf2); return __builtin_bit_cast(unsigned, r); }
;     __device__ __forceinline__ void operator()(const f32x4 (&acc)[2][2][4][2], const Unit& u, int wr, int wc, int fr, int fq) const {
;     ...
;                     u32x4 w; w.x = pk2(v0[0], v0[1]); w.y = pk2(v0[2], v0[3]); w.z = pk2(v1[0], v1[1]); w.w = pk2(v1[2], v1[3]);
;                     *(u32x4*)(dst + off + bj * 128) = w;
;                     if (fo) { __builtin_nontemporal_store(v0, (f32x4*)(fo + off + bj * 128)); __builtin_nontemporal_store(v1, (f32x4*)(fo + off + bj * 128 + 4)); }
.LBB0_205:
	v_cvt_pk_bf16_f32 v24, v20, v21
	v_cvt_pk_bf16_f32 v25, v22, v23
	v_cvt_pk_bf16_f32 v26, v16, v17
	v_cvt_pk_bf16_f32 v27, v18, v19
	global_store_dwordx4 v[34:35], v[24:27], off offset:256
	s_and_saveexec_b64 s[40:41], s[8:9]
	s_cbranch_execz .LBB0_207
	s_nop 1
	v_permlane16_swap_b32_e32 v20, v16
	v_permlane16_swap_b32_e32 v21, v17
	v_permlane16_swap_b32_e32 v22, v18
	v_permlane16_swap_b32_e32 v23, v19
	v_permlane32_swap_b32_e32 v20, v16
	v_permlane32_swap_b32_e32 v21, v17
	v_permlane32_swap_b32_e32 v22, v18
	v_permlane32_swap_b32_e32 v23, v19
	v_lshl_add_u64 v[202:203], v[32:33], 0, v[200:201]
	global_store_dwordx4 v[202:203], v[20:23], off offset:512
	global_store_dwordx4 v[202:203], v[16:19], off offset:576

; __device__ __forceinline__ unsigned pk2(float lo, float hi) { f32x2 v = {lo, hi}; hbf2 r = __builtin_convertvector(v, hbf2); return __builtin_bit_cast(unsigned, r); }
;     __device__ __forceinline__ void operator()(const f32x4 (&acc)[2][2][4][2], const Unit& u, int wr, int wc, int fr, int fq) const {
;     ...
;                 const size_t off = (size_t)(row0 + ai * 128 + m * 16) * HW + cb;
; #pragma unroll
;                 for (int bj = 0; bj < 2; ++bj) {
;                     f32x4 v0 = acc[ai][bj][m][0], v1 = acc[ai][bj][m][1];
;                     if (sect == 0) { v0 = v0 * 0.125f; v1 = v1 * 0.125f; }
;                     if (sect >= 3) {
; #pragma unroll
;                         for (int e = 0; e < 4; ++e) { v0[e] = gelu_t(v0[e]); v1[e] = gelu_t(v1[e]); }
;                     }
;                     u32x4 w; w.x = pk2(v0[0], v0[1]); w.y = pk2(v0[2], v0[3]); w.z = pk2(v1[0], v1[1]); w.w = pk2(v1[2], v1[3]);
;                     *(u32x4*)(dst + off + bj * 128) = w;
;                     if (fo) { __builtin_nontemporal_store(v0, (f32x4*)(fo + off + bj * 128)); __builtin_nontemporal_store(v1, (f32x4*)(fo + off + bj * 128 + 4)); }
.LBB0_209:
	v_lshlrev_b64 v[16:17], 9, v[146:147]
	v_or_b32_e32 v16, v16, v170
	v_lshl_add_u64 v[16:17], v[16:17], 0, s[26:27]
	v_lshl_add_u64 v[18:19], v[16:17], 1, s[38:39]
	v_lshl_add_u64 v[16:17], v[16:17], 2, v[148:149]
	v_cvt_pk_bf16_f32 v20, v12, v13
	v_cvt_pk_bf16_f32 v21, v14, v15
	v_cvt_pk_bf16_f32 v22, v8, v9
	v_cvt_pk_bf16_f32 v23, v10, v11
	global_store_dwordx4 v[18:19], v[20:23], off
	s_and_saveexec_b64 s[38:39], s[8:9]
	s_cbranch_execz .LBB0_211
	s_nop 1
	v_permlane16_swap_b32_e32 v12, v8
	v_permlane16_swap_b32_e32 v13, v9
	v_permlane16_swap_b32_e32 v14, v10
	v_permlane16_swap_b32_e32 v15, v11
	v_permlane32_swap_b32_e32 v12, v8
	v_permlane32_swap_b32_e32 v13, v9
	v_permlane32_swap_b32_e32 v14, v10
	v_permlane32_swap_b32_e32 v15, v11
	v_lshl_add_u64 v[202:203], v[16:17], 0, v[200:201]
	global_store_dwordx4 v[202:203], v[12:15], off
	global_store_dwordx4 v[202:203], v[8:11], off offset:64

; __device__ __forceinline__ unsigned pk2(float lo, float hi) { f32x2 v = {lo, hi}; hbf2 r = __builtin_convertvector(v, hbf2); return __builtin_bit_cast(unsigned, r); }
;     __device__ __forceinline__ void operator()(const f32x4 (&acc)[2][2][4][2], const Unit& u, int wr, int wc, int fr, int fq) const {
;     ...
;                     u32x4 w; w.x = pk2(v0[0], v0[1]); w.y = pk2(v0[2], v0[3]); w.z = pk2(v1[0], v1[1]); w.w = pk2(v1[2], v1[3]);
;                     *(u32x4*)(dst + off + bj * 128) = w;
;                     if (fo) { __builtin_nontemporal_store(v0, (f32x4*)(fo + off + bj * 128)); __builtin_nontemporal_store(v1, (f32x4*)(fo + off + bj * 128 + 4)); }
.LBB0_213:
	v_cvt_pk_bf16_f32 v8, v4, v5
	v_cvt_pk_bf16_f32 v9, v6, v7
	v_cvt_pk_bf16_f32 v10, v0, v1
	v_cvt_pk_bf16_f32 v11, v2, v3
	global_store_dwordx4 v[18:19], v[8:11], off offset:256
	s_and_saveexec_b64 s[6:7], s[8:9]
	s_cbranch_execz .LBB0_215
	s_nop 1
	v_permlane16_swap_b32_e32 v4, v0
	v_permlane16_swap_b32_e32 v5, v1
	v_permlane16_swap_b32_e32 v6, v2
	v_permlane16_swap_b32_e32 v7, v3
	v_permlane32_swap_b32_e32 v4, v0
	v_permlane32_swap_b32_e32 v5, v1
	v_permlane32_swap_b32_e32 v6, v2
	v_permlane32_swap_b32_e32 v7, v3
	v_lshl_add_u64 v[202:203], v[16:17], 0, v[200:201]
	global_store_dwordx4 v[202:203], v[4:7], off offset:512
	global_store_dwordx4 v[202:203], v[0:3], off offset:576
